# attention: V transpose reads issued two per QK MFMA gap instead of as a burst after the MFMAs
# baseline (speedup 1.0000x reference)
.LBB0_789:
	v_exp_f32_e32 v37, v192
	v_exp_f32_e32 v38, v196
	v_exp_f32_e32 v39, v193
	v_exp_f32_e32 v196, v197
	v_exp_f32_e32 v193, v194
	v_exp_f32_e32 v194, v195
	v_cvt_pk_bf16_f32 v192, v37, v39
	v_exp_f32_e32 v37, v180
	v_exp_f32_e32 v39, v181
	v_cvt_pk_bf16_f32 v193, v193, v194
	v_cvt_pk_bf16_f32 v194, v38, v196
	v_exp_f32_e32 v38, v188
	v_exp_f32_e32 v188, v189
	v_exp_f32_e32 v181, v182
	v_exp_f32_e32 v182, v183
	v_exp_f32_e32 v197, v198
	v_exp_f32_e32 v195, v199
	v_cvt_pk_bf16_f32 v180, v37, v39
	v_cvt_pk_bf16_f32 v181, v181, v182
	v_cvt_pk_bf16_f32 v182, v38, v188
	v_exp_f32_e32 v37, v156
	v_exp_f32_e32 v38, v184
	v_exp_f32_e32 v39, v157
	v_exp_f32_e32 v184, v185
	v_exp_f32_e32 v157, v158
	v_exp_f32_e32 v158, v159
	s_mov_b32 s62, s60
	s_mov_b32 s63, s60
	v_cvt_pk_bf16_f32 v195, v197, v195
	s_mov_b32 s61, s60
	v_mov_b64_e32 v[198:199], s[62:63]
	v_mov_b64_e32 v[196:197], s[60:61]
	v_exp_f32_e32 v189, v190
	v_exp_f32_e32 v183, v191
	v_exp_f32_e32 v185, v186
	v_exp_f32_e32 v159, v187
	v_cvt_pk_bf16_f32 v156, v37, v39
	v_cvt_pk_bf16_f32 v157, v157, v158
	v_cvt_pk_bf16_f32 v158, v38, v184
	v_exp_f32_e32 v37, v152
	v_exp_f32_e32 v38, v172
	v_exp_f32_e32 v39, v153
	v_exp_f32_e32 v172, v173
	v_exp_f32_e32 v153, v154
	v_exp_f32_e32 v173, v174
	v_exp_f32_e32 v154, v155
	v_exp_f32_e32 v155, v175
	v_cvt_pk_bf16_f32 v183, v189, v183
	v_cvt_pk_bf16_f32 v159, v185, v159
	v_cvt_pk_bf16_f32 v152, v37, v39
	v_cvt_pk_bf16_f32 v153, v153, v154
	v_cvt_pk_bf16_f32 v154, v38, v172
	v_cvt_pk_bf16_f32 v155, v173, v155
	v_mfma_f32_16x16x32_bf16 v[116:119], v[196:199], v[192:195], v[116:119]
	v_subrev_u32_e32 v34, s73, v34
	v_add_u32_e32 v35, 0x1400, v35
	s_andn2_b64 vcc, exec, s[34:35]
	v_mfma_f32_16x16x32_bf16 v[64:67], v[196:199], v[180:183], v[64:67]
	v_mfma_f32_16x16x32_bf16 v[44:47], v[196:199], v[156:159], v[44:47]
	v_mfma_f32_16x16x32_bf16 v[16:19], v[196:199], v[152:155], v[16:19]
	s_waitcnt lgkmcnt(10)
	v_mfma_f32_16x16x32_bf16 v[96:99], v[168:171], v[192:195], v[96:99]
	v_mfma_f32_16x16x32_bf16 v[60:63], v[168:171], v[180:183], v[60:63]
	v_mfma_f32_16x16x32_bf16 v[40:43], v[168:171], v[156:159], v[40:43]
	v_mfma_f32_16x16x32_bf16 v[8:11], v[168:171], v[152:155], v[8:11]
	s_waitcnt lgkmcnt(8)
	v_mfma_f32_16x16x32_bf16 v[68:71], v[160:163], v[192:195], v[68:71]
	v_mfma_f32_16x16x32_bf16 v[48:51], v[160:163], v[180:183], v[48:51]
	v_mfma_f32_16x16x32_bf16 v[20:23], v[160:163], v[156:159], v[20:23]
	v_mfma_f32_16x16x32_bf16 v[0:3], v[160:163], v[152:155], v[0:3]
	s_waitcnt lgkmcnt(6)
	v_mfma_f32_16x16x32_bf16 v[92:95], v[176:179], v[192:195], v[92:95]
	v_mfma_f32_16x16x32_bf16 v[56:59], v[176:179], v[180:183], v[56:59]
	v_mfma_f32_16x16x32_bf16 v[28:31], v[176:179], v[156:159], v[28:31]
	v_mfma_f32_16x16x32_bf16 v[12:15], v[176:179], v[152:155], v[12:15]
	s_waitcnt lgkmcnt(4)
	v_mfma_f32_16x16x32_bf16 v[80:83], v[164:167], v[192:195], v[80:83]
	v_mfma_f32_16x16x32_bf16 v[52:55], v[164:167], v[180:183], v[52:55]
	v_mfma_f32_16x16x32_bf16 v[24:27], v[164:167], v[156:159], v[24:27]
	v_mfma_f32_16x16x32_bf16 v[4:7], v[164:167], v[152:155], v[4:7]
	s_cbranch_vccz .LBB0_801
.LBB0_790:
	s_waitcnt lgkmcnt(3)
	v_mfma_f32_16x16x32_bf16 v[152:155], v[144:147], v[72:75], v[228:231]
	s_waitcnt lgkmcnt(2)
	v_mfma_f32_16x16x32_bf16 v[192:195], v[148:151], v[76:79], v[152:155]
	v_mfma_f32_16x16x32_bf16 v[152:155], v[144:147], v[84:87], v[232:235]
	v_mfma_f32_16x16x32_bf16 v[180:183], v[148:151], v[88:91], v[152:155]
	s_mov_b32 s6, s53
	s_add_i32 s53, s53, 1
	s_cmp_ge_u32 s53, s52
	v_mfma_f32_16x16x32_bf16 v[152:155], v[144:147], v[100:103], v[248:251]
	s_cselect_b64 s[34:35], -1, 0
	s_cmp_lt_u32 s53, s52
	s_cselect_b32 s6, s53, s6
	v_mfma_f32_16x16x32_bf16 v[144:147], v[144:147], v[108:111], v[220:223]
	v_lshl_or_b32 v37, s6, 5, v201
	v_mad_u32_u24 v38, v37, s3, v32
	v_mfma_f32_16x16x32_bf16 v[156:159], v[148:151], v[104:107], v[152:155]
	v_mfma_f32_16x16x32_bf16 v[152:155], v[148:151], v[112:115], v[144:147]
	s_waitcnt lgkmcnt(1)
	v_mfma_f32_16x16x32_bf16 v[144:147], v[140:143], v[72:75], v[228:231]
	s_waitcnt lgkmcnt(0)
	v_mfma_f32_16x16x32_bf16 v[196:199], v[136:139], v[76:79], v[144:147]
	ds_read_b64_tr_b16 v[168:169], v35
	ds_read_b64_tr_b16 v[170:171], v35 offset:2560
	v_mfma_f32_16x16x32_bf16 v[144:147], v[140:143], v[84:87], v[232:235]
	ds_read_b64_tr_b16 v[160:161], v35 offset:32
	ds_read_b64_tr_b16 v[162:163], v35 offset:2592
	v_mfma_f32_16x16x32_bf16 v[188:191], v[136:139], v[88:91], v[144:147]
	ds_read_b64_tr_b16 v[176:177], v35 offset:64
	ds_read_b64_tr_b16 v[178:179], v35 offset:2624
	v_mfma_f32_16x16x32_bf16 v[144:147], v[140:143], v[100:103], v[248:251]
	ds_read_b64_tr_b16 v[164:165], v35 offset:96
	ds_read_b64_tr_b16 v[166:167], v35 offset:2656
	v_mfma_f32_16x16x32_bf16 v[140:143], v[140:143], v[108:111], v[220:223]
	v_mfma_f32_16x16x32_bf16 v[184:187], v[136:139], v[104:107], v[144:147]
	s_nop 5
	ds_read_b128 v[144:147], v38
	ds_read_b128 v[148:151], v38 offset:64
	v_mfma_f32_16x16x32_bf16 v[172:175], v[136:139], v[112:115], v[140:143]
	s_nop 2
	ds_read_b128 v[140:143], v38 offset:2304
	ds_read_b128 v[136:139], v38 offset:2368
	s_andn2_b64 vcc, exec, s[86:87]
	s_cbranch_vccnz .LBB0_792
